# previous best + second saddr pass: B-operand pointer pairs and the last simple sA+vO site in the four row-major GEMM loops now use SGPR-base DMAs (5 more VALU adds removed per iteration)
# baseline (speedup 1.0000x reference)
.LBB0_101:
	ds_read_b128 v[154:157], v151
	ds_read_b128 v[158:161], v151 offset:1024
	ds_read_b128 v[162:165], v151 offset:2048
	ds_read_b128 v[166:169], v151 offset:3072
	ds_read_b128 v[170:173], v152
	ds_read_b128 v[174:177], v152 offset:1024
	ds_read_b128 v[188:191], v152 offset:2048
	ds_read_b128 v[192:195], v152 offset:3072
	s_add_u32 s40, s36, s38
	s_addc_u32 s41, s37, s39
	s_add_u32 s44, s40, 0x100
	s_addc_u32 s45, s41, 0
	s_add_u32 s42, s66, s38
	s_addc_u32 s43, s67, s39
	s_add_u32 s40, s40, 0x180
	s_addc_u32 s41, s41, 0
	s_cmpk_eq_i32 s38, 0x1f00
	s_cselect_b32 s41, s65, s41
	s_cselect_b32 s40, s64, s40
	s_cselect_b32 s43, s35, s43
	s_cselect_b32 s42, s34, s42
	s_cselect_b32 s45, s23, s45
	s_cselect_b32 s44, s22, s44
	s_mov_b32 m0, s57
	v_lshl_add_u64 v[178:179], v[146:147], 0, s[38:39]
	ds_read_b128 v[196:199], v153
	ds_read_b128 v[200:203], v153 offset:1024
	ds_read_b128 v[204:207], v153 offset:2048
	ds_read_b128 v[208:211], v153 offset:3072
	ds_read_b128 v[214:217], v153 offset:4096
	ds_read_b128 v[218:221], v153 offset:5120
	ds_read_b128 v[222:225], v153 offset:6144
	ds_read_b128 v[226:229], v153 offset:7168
	global_load_lds_dwordx4 v[178:179], off
	v_lshl_add_u64 v[178:179], v[148:149], 0, s[38:39]
	s_add_i32 m0, s47, 0xe000
	s_nop 0
	global_load_lds_dwordx4 v[178:179], off
	s_waitcnt vmcnt(8)
	s_waitcnt lgkmcnt(0)
	s_barrier
	s_waitcnt lgkmcnt(0)
	v_mfma_f32_16x16x32_bf16 v[126:129], v[154:157], v[196:199], v[126:129]
	v_mfma_f32_16x16x32_bf16 v[126:129], v[158:161], v[200:203], v[126:129]
	v_mfma_f32_16x16x32_bf16 v[122:125], v[166:169], v[200:203], v[122:125]
	v_mfma_f32_16x16x32_bf16 v[122:125], v[162:165], v[196:199], v[122:125]
	v_mfma_f32_16x16x32_bf16 v[110:113], v[162:165], v[204:207], v[110:113]
	v_mfma_f32_16x16x32_bf16 v[110:113], v[166:169], v[208:211], v[110:113]
	v_mfma_f32_16x16x32_bf16 v[118:121], v[158:161], v[208:211], v[118:121]
	v_mfma_f32_16x16x32_bf16 v[118:121], v[154:157], v[204:207], v[118:121]
	v_mfma_f32_16x16x32_bf16 v[102:105], v[154:157], v[214:217], v[102:105]
	v_mfma_f32_16x16x32_bf16 v[102:105], v[158:161], v[218:221], v[102:105]
	v_mfma_f32_16x16x32_bf16 v[94:97], v[166:169], v[218:221], v[94:97]
	v_mfma_f32_16x16x32_bf16 v[94:97], v[162:165], v[214:217], v[94:97]
	v_mfma_f32_16x16x32_bf16 v[78:81], v[162:165], v[222:225], v[78:81]
	v_mfma_f32_16x16x32_bf16 v[78:81], v[166:169], v[226:229], v[78:81]
	v_mfma_f32_16x16x32_bf16 v[86:89], v[158:161], v[226:229], v[86:89]
	v_mfma_f32_16x16x32_bf16 v[86:89], v[154:157], v[222:225], v[86:89]
	v_mfma_f32_16x16x32_bf16 v[114:117], v[170:173], v[196:199], v[114:117]
	v_mfma_f32_16x16x32_bf16 v[114:117], v[174:177], v[200:203], v[114:117]
	v_mfma_f32_16x16x32_bf16 v[106:109], v[192:195], v[200:203], v[106:109]
	v_mfma_f32_16x16x32_bf16 v[106:109], v[188:191], v[196:199], v[106:109]
	v_mfma_f32_16x16x32_bf16 v[90:93], v[188:191], v[204:207], v[90:93]
	v_mfma_f32_16x16x32_bf16 v[90:93], v[192:195], v[208:211], v[90:93]
	v_mfma_f32_16x16x32_bf16 v[98:101], v[174:177], v[208:211], v[98:101]
	v_mfma_f32_16x16x32_bf16 v[98:101], v[170:173], v[204:207], v[98:101]
	v_mfma_f32_16x16x32_bf16 v[82:85], v[170:173], v[214:217], v[82:85]
	v_mfma_f32_16x16x32_bf16 v[82:85], v[174:177], v[218:221], v[82:85]
	v_mfma_f32_16x16x32_bf16 v[74:77], v[192:195], v[218:221], v[74:77]
	v_mfma_f32_16x16x32_bf16 v[74:77], v[188:191], v[214:217], v[74:77]
	v_mfma_f32_16x16x32_bf16 v[66:69], v[188:191], v[222:225], v[66:69]
	v_mfma_f32_16x16x32_bf16 v[66:69], v[192:195], v[226:229], v[66:69]
	v_mfma_f32_16x16x32_bf16 v[70:73], v[174:177], v[226:229], v[70:73]
	v_mfma_f32_16x16x32_bf16 v[70:73], v[170:173], v[222:225], v[70:73]
	s_barrier
	s_add_i32 s69, s54, s3
	s_mov_b32 m0, s69
	ds_read_b128 v[196:199], v153 offset:16384
	ds_read_b128 v[200:203], v153 offset:17408
	ds_read_b128 v[204:207], v153 offset:18432
	ds_read_b128 v[208:211], v153 offset:19456
	ds_read_b128 v[214:217], v153 offset:20480
	ds_read_b128 v[218:221], v153 offset:21504
	ds_read_b128 v[222:225], v153 offset:22528
	ds_read_b128 v[226:229], v153 offset:23552
	global_load_lds_dwordx4 v136, s[42:43]
	s_add_i32 m0, s69, 0x2000
	s_add_u32 s70, s42, 0x108000
	s_addc_u32 s71, s43, 0
	s_add_i32 s69, s55, s3
	global_load_lds_dwordx4 v140, s[42:43]
	s_mov_b32 m0, s69
	s_nop 0
	global_load_lds_dwordx4 v136, s[70:71]
	s_add_i32 m0, s69, 0x2000
	s_nop 0
	global_load_lds_dwordx4 v140, s[70:71]
	s_mov_b32 m0, s47
	s_nop 0
	global_load_lds_dwordx4 v134, s[44:45]
	s_mov_b32 m0, s48
	s_nop 0
	global_load_lds_dwordx4 v138, s[44:45]
	s_waitcnt vmcnt(8)
	s_waitcnt lgkmcnt(0)
	s_barrier
	s_waitcnt lgkmcnt(0)
	v_mfma_f32_16x16x32_bf16 v[62:65], v[154:157], v[196:199], v[62:65]
	v_mfma_f32_16x16x32_bf16 v[62:65], v[158:161], v[200:203], v[62:65]
	v_mfma_f32_16x16x32_bf16 v[58:61], v[166:169], v[200:203], v[58:61]
	v_mfma_f32_16x16x32_bf16 v[58:61], v[162:165], v[196:199], v[58:61]
	v_mfma_f32_16x16x32_bf16 v[46:49], v[162:165], v[204:207], v[46:49]
	v_mfma_f32_16x16x32_bf16 v[46:49], v[166:169], v[208:211], v[46:49]
	v_mfma_f32_16x16x32_bf16 v[54:57], v[158:161], v[208:211], v[54:57]
	v_mfma_f32_16x16x32_bf16 v[54:57], v[154:157], v[204:207], v[54:57]
	v_mfma_f32_16x16x32_bf16 v[38:41], v[154:157], v[214:217], v[38:41]
	v_mfma_f32_16x16x32_bf16 v[38:41], v[158:161], v[218:221], v[38:41]
	v_mfma_f32_16x16x32_bf16 v[30:33], v[166:169], v[218:221], v[30:33]
	v_mfma_f32_16x16x32_bf16 v[30:33], v[162:165], v[214:217], v[30:33]
	v_mfma_f32_16x16x32_bf16 v[14:17], v[162:165], v[222:225], v[14:17]
	v_mfma_f32_16x16x32_bf16 v[14:17], v[166:169], v[226:229], v[14:17]
	v_mfma_f32_16x16x32_bf16 v[22:25], v[158:161], v[226:229], v[22:25]
	v_mfma_f32_16x16x32_bf16 v[22:25], v[154:157], v[222:225], v[22:25]
	v_mfma_f32_16x16x32_bf16 v[50:53], v[170:173], v[196:199], v[50:53]
	v_mfma_f32_16x16x32_bf16 v[50:53], v[174:177], v[200:203], v[50:53]
	v_mfma_f32_16x16x32_bf16 v[42:45], v[192:195], v[200:203], v[42:45]
	v_mfma_f32_16x16x32_bf16 v[42:45], v[188:191], v[196:199], v[42:45]
	v_mfma_f32_16x16x32_bf16 v[26:29], v[188:191], v[204:207], v[26:29]
	v_mfma_f32_16x16x32_bf16 v[26:29], v[192:195], v[208:211], v[26:29]
	v_mfma_f32_16x16x32_bf16 v[34:37], v[174:177], v[208:211], v[34:37]
	v_mfma_f32_16x16x32_bf16 v[34:37], v[170:173], v[204:207], v[34:37]
	v_mfma_f32_16x16x32_bf16 v[18:21], v[170:173], v[214:217], v[18:21]
	v_mfma_f32_16x16x32_bf16 v[18:21], v[174:177], v[218:221], v[18:21]
	v_mfma_f32_16x16x32_bf16 v[10:13], v[192:195], v[218:221], v[10:13]
	v_mfma_f32_16x16x32_bf16 v[10:13], v[188:191], v[214:217], v[10:13]
	v_mfma_f32_16x16x32_bf16 v[2:5], v[188:191], v[222:225], v[2:5]
	v_mfma_f32_16x16x32_bf16 v[2:5], v[192:195], v[226:229], v[2:5]
	v_mfma_f32_16x16x32_bf16 v[6:9], v[174:177], v[226:229], v[6:9]
	v_mfma_f32_16x16x32_bf16 v[6:9], v[170:173], v[222:225], v[6:9]
	s_barrier
	s_add_i32 s69, 0, 0x18000
	s_add_i32 s70, 0, 0x1c000
	v_add_u32_e32 v166, s69, v133
	v_add_u32_e32 v187, s70, v133
	ds_read_b128 v[154:157], v166
	ds_read_b128 v[158:161], v166 offset:1024
	ds_read_b128 v[162:165], v166 offset:2048
	ds_read_b128 v[166:169], v166 offset:3072
	ds_read_b128 v[170:173], v187
	ds_read_b128 v[174:177], v187 offset:1024
	ds_read_b128 v[188:191], v187 offset:2048
	ds_read_b128 v[192:195], v187 offset:3072
	s_add_u32 s44, s44, 0x108000
	s_addc_u32 s45, s45, 0
	s_mov_b32 m0, s49
	ds_read_b128 v[196:199], v153 offset:32768
	ds_read_b128 v[200:203], v153 offset:33792
	ds_read_b128 v[204:207], v153 offset:34816
	ds_read_b128 v[208:211], v153 offset:35840
	ds_read_b128 v[214:217], v153 offset:36864
	ds_read_b128 v[218:221], v153 offset:37888
	ds_read_b128 v[222:225], v153 offset:38912
	ds_read_b128 v[226:229], v153 offset:39936
	global_load_lds_dwordx4 v134, s[44:45]
	s_mov_b32 m0, s50
	s_nop 0
	global_load_lds_dwordx4 v138, s[44:45]
	s_waitcnt vmcnt(8)
	s_waitcnt lgkmcnt(0)
	s_barrier
	s_waitcnt lgkmcnt(0)
	v_mfma_f32_16x16x32_bf16 v[126:129], v[154:157], v[196:199], v[126:129]
	v_mfma_f32_16x16x32_bf16 v[126:129], v[158:161], v[200:203], v[126:129]
	v_mfma_f32_16x16x32_bf16 v[122:125], v[166:169], v[200:203], v[122:125]
	v_mfma_f32_16x16x32_bf16 v[122:125], v[162:165], v[196:199], v[122:125]
	v_mfma_f32_16x16x32_bf16 v[110:113], v[162:165], v[204:207], v[110:113]
	v_mfma_f32_16x16x32_bf16 v[110:113], v[166:169], v[208:211], v[110:113]
	v_mfma_f32_16x16x32_bf16 v[118:121], v[158:161], v[208:211], v[118:121]
	v_mfma_f32_16x16x32_bf16 v[118:121], v[154:157], v[204:207], v[118:121]
	v_mfma_f32_16x16x32_bf16 v[102:105], v[154:157], v[214:217], v[102:105]
	v_mfma_f32_16x16x32_bf16 v[102:105], v[158:161], v[218:221], v[102:105]
	v_mfma_f32_16x16x32_bf16 v[94:97], v[166:169], v[218:221], v[94:97]
	v_mfma_f32_16x16x32_bf16 v[94:97], v[162:165], v[214:217], v[94:97]
	v_mfma_f32_16x16x32_bf16 v[78:81], v[162:165], v[222:225], v[78:81]
	v_mfma_f32_16x16x32_bf16 v[78:81], v[166:169], v[226:229], v[78:81]
	v_mfma_f32_16x16x32_bf16 v[86:89], v[158:161], v[226:229], v[86:89]
	v_mfma_f32_16x16x32_bf16 v[86:89], v[154:157], v[222:225], v[86:89]
	v_mfma_f32_16x16x32_bf16 v[114:117], v[170:173], v[196:199], v[114:117]
	v_mfma_f32_16x16x32_bf16 v[114:117], v[174:177], v[200:203], v[114:117]
	v_mfma_f32_16x16x32_bf16 v[106:109], v[192:195], v[200:203], v[106:109]
	v_mfma_f32_16x16x32_bf16 v[106:109], v[188:191], v[196:199], v[106:109]
	v_mfma_f32_16x16x32_bf16 v[90:93], v[188:191], v[204:207], v[90:93]
	v_mfma_f32_16x16x32_bf16 v[90:93], v[192:195], v[208:211], v[90:93]
	v_mfma_f32_16x16x32_bf16 v[98:101], v[174:177], v[208:211], v[98:101]
	v_mfma_f32_16x16x32_bf16 v[98:101], v[170:173], v[204:207], v[98:101]
	v_mfma_f32_16x16x32_bf16 v[82:85], v[170:173], v[214:217], v[82:85]
	v_mfma_f32_16x16x32_bf16 v[82:85], v[174:177], v[218:221], v[82:85]
	v_mfma_f32_16x16x32_bf16 v[74:77], v[192:195], v[218:221], v[74:77]
	v_mfma_f32_16x16x32_bf16 v[74:77], v[188:191], v[214:217], v[74:77]
	v_mfma_f32_16x16x32_bf16 v[66:69], v[188:191], v[222:225], v[66:69]
	v_mfma_f32_16x16x32_bf16 v[66:69], v[192:195], v[226:229], v[66:69]
	v_mfma_f32_16x16x32_bf16 v[70:73], v[174:177], v[226:229], v[70:73]
	v_mfma_f32_16x16x32_bf16 v[70:73], v[170:173], v[222:225], v[70:73]
	s_barrier
	s_add_i32 s44, s69, s3
	s_add_u32 s42, s42, 0x80
	s_addc_u32 s43, s43, 0
	s_mov_b32 m0, s44
	ds_read_b128 v[196:199], v153 offset:49152
	ds_read_b128 v[200:203], v153 offset:50176
	ds_read_b128 v[204:207], v153 offset:51200
	ds_read_b128 v[208:211], v153 offset:52224
	ds_read_b128 v[214:217], v153 offset:53248
	ds_read_b128 v[218:221], v153 offset:54272
	ds_read_b128 v[222:225], v153 offset:55296
	ds_read_b128 v[226:229], v153 offset:56320
	global_load_lds_dwordx4 v136, s[42:43]
	s_add_i32 m0, s44, 0x2000
	s_add_i32 s44, s70, s3
	global_load_lds_dwordx4 v140, s[42:43]
	s_add_u32 s42, s42, 0x108000
	s_addc_u32 s43, s43, 0
	s_mov_b32 m0, s44
	s_nop 0
	global_load_lds_dwordx4 v136, s[42:43]
	s_add_i32 m0, s44, 0x2000
	s_nop 0
	global_load_lds_dwordx4 v140, s[42:43]
	s_mov_b32 m0, s52
	s_nop 0
	global_load_lds_dwordx4 v134, s[40:41]
	s_mov_b32 m0, s53
	s_nop 0
	global_load_lds_dwordx4 v138, s[40:41]
	s_waitcnt vmcnt(8)
	s_waitcnt lgkmcnt(0)
	s_barrier
	s_waitcnt lgkmcnt(0)
	v_mfma_f32_16x16x32_bf16 v[62:65], v[154:157], v[196:199], v[62:65]
	v_mfma_f32_16x16x32_bf16 v[62:65], v[158:161], v[200:203], v[62:65]
	v_mfma_f32_16x16x32_bf16 v[58:61], v[166:169], v[200:203], v[58:61]
	v_mfma_f32_16x16x32_bf16 v[58:61], v[162:165], v[196:199], v[58:61]
	v_mfma_f32_16x16x32_bf16 v[46:49], v[162:165], v[204:207], v[46:49]
	v_mfma_f32_16x16x32_bf16 v[46:49], v[166:169], v[208:211], v[46:49]
	v_mfma_f32_16x16x32_bf16 v[54:57], v[158:161], v[208:211], v[54:57]
	v_mfma_f32_16x16x32_bf16 v[54:57], v[154:157], v[204:207], v[54:57]
	v_mfma_f32_16x16x32_bf16 v[38:41], v[154:157], v[214:217], v[38:41]
	v_mfma_f32_16x16x32_bf16 v[38:41], v[158:161], v[218:221], v[38:41]
	v_mfma_f32_16x16x32_bf16 v[30:33], v[166:169], v[218:221], v[30:33]
	v_mfma_f32_16x16x32_bf16 v[30:33], v[162:165], v[214:217], v[30:33]
	v_mfma_f32_16x16x32_bf16 v[14:17], v[162:165], v[222:225], v[14:17]
	v_mfma_f32_16x16x32_bf16 v[14:17], v[166:169], v[226:229], v[14:17]
	v_mfma_f32_16x16x32_bf16 v[22:25], v[158:161], v[226:229], v[22:25]
	v_mfma_f32_16x16x32_bf16 v[22:25], v[154:157], v[222:225], v[22:25]
	v_mfma_f32_16x16x32_bf16 v[50:53], v[170:173], v[196:199], v[50:53]
	v_mfma_f32_16x16x32_bf16 v[50:53], v[174:177], v[200:203], v[50:53]
	v_mfma_f32_16x16x32_bf16 v[42:45], v[192:195], v[200:203], v[42:45]
	v_mfma_f32_16x16x32_bf16 v[42:45], v[188:191], v[196:199], v[42:45]
	v_mfma_f32_16x16x32_bf16 v[26:29], v[188:191], v[204:207], v[26:29]
	v_mfma_f32_16x16x32_bf16 v[26:29], v[192:195], v[208:211], v[26:29]
	v_mfma_f32_16x16x32_bf16 v[34:37], v[174:177], v[208:211], v[34:37]
	v_mfma_f32_16x16x32_bf16 v[34:37], v[170:173], v[204:207], v[34:37]
	v_mfma_f32_16x16x32_bf16 v[18:21], v[170:173], v[214:217], v[18:21]
	v_mfma_f32_16x16x32_bf16 v[18:21], v[174:177], v[218:221], v[18:21]
	v_mfma_f32_16x16x32_bf16 v[10:13], v[192:195], v[218:221], v[10:13]
	v_mfma_f32_16x16x32_bf16 v[10:13], v[188:191], v[214:217], v[10:13]
	v_mfma_f32_16x16x32_bf16 v[2:5], v[188:191], v[222:225], v[2:5]
	v_mfma_f32_16x16x32_bf16 v[2:5], v[192:195], v[226:229], v[2:5]
	v_mfma_f32_16x16x32_bf16 v[6:9], v[174:177], v[226:229], v[6:9]
	v_mfma_f32_16x16x32_bf16 v[6:9], v[170:173], v[222:225], v[6:9]
	s_barrier
	s_add_i32 s68, s68, 2
	s_add_u32 s38, s38, 0x100
	s_addc_u32 s39, s39, 0
	s_cmp_gt_u32 s68, 61
	s_cbranch_scc0 .LBB0_101
	s_and_b64 vcc, exec, s[20:21]
	s_cbranch_vccz .LBB0_104
	s_barrier

.LBB0_235:
	ds_read_b128 v[156:159], v150
	ds_read_b128 v[160:163], v150 offset:1024
	ds_read_b128 v[164:167], v150 offset:2048
	ds_read_b128 v[168:171], v150 offset:3072
	ds_read_b128 v[172:175], v151
	ds_read_b128 v[176:179], v151 offset:1024
	ds_read_b128 v[180:183], v151 offset:2048
	ds_read_b128 v[184:187], v151 offset:3072
	s_add_u32 s36, s4, s34
	s_addc_u32 s37, s5, s35
	s_add_u32 s40, s36, 0x100
	s_addc_u32 s41, s37, 0
	s_add_u32 s38, s62, s34
	s_addc_u32 s39, s63, s35
	s_add_u32 s36, s36, 0x180
	s_addc_u32 s37, s37, 0
	s_cmpk_eq_i32 s34, 0x1f00
	s_cselect_b32 s37, s61, s37
	s_cselect_b32 s36, s60, s36
	s_cselect_b32 s39, s31, s39
	s_cselect_b32 s38, s30, s38
	s_cselect_b32 s41, s23, s41
	s_cselect_b32 s40, s22, s40
	s_mov_b32 m0, s46
	v_lshl_add_u64 v[222:223], v[146:147], 0, s[34:35]
	ds_read_b128 v[188:191], v152
	ds_read_b128 v[192:195], v152 offset:1024
	ds_read_b128 v[196:199], v152 offset:2048
	ds_read_b128 v[200:203], v152 offset:3072
	ds_read_b128 v[204:207], v152 offset:4096
	ds_read_b128 v[208:211], v152 offset:5120
	ds_read_b128 v[214:217], v152 offset:6144
	ds_read_b128 v[218:221], v152 offset:7168
	global_load_lds_dwordx4 v[222:223], off
	v_lshl_add_u64 v[222:223], v[148:149], 0, s[34:35]
	s_mov_b32 m0, s47
	s_nop 0
	global_load_lds_dwordx4 v[222:223], off
	s_waitcnt vmcnt(8)
	s_waitcnt lgkmcnt(0)
	s_barrier
	s_waitcnt lgkmcnt(0)
	v_mfma_f32_16x16x32_bf16 v[126:129], v[156:159], v[188:191], v[126:129]
	v_mfma_f32_16x16x32_bf16 v[126:129], v[160:163], v[192:195], v[126:129]
	v_mfma_f32_16x16x32_bf16 v[122:125], v[168:171], v[192:195], v[122:125]
	v_mfma_f32_16x16x32_bf16 v[122:125], v[164:167], v[188:191], v[122:125]
	v_mfma_f32_16x16x32_bf16 v[106:109], v[164:167], v[196:199], v[106:109]
	v_mfma_f32_16x16x32_bf16 v[106:109], v[168:171], v[200:203], v[106:109]
	v_mfma_f32_16x16x32_bf16 v[110:113], v[160:163], v[200:203], v[110:113]
	v_mfma_f32_16x16x32_bf16 v[110:113], v[156:159], v[196:199], v[110:113]
	v_mfma_f32_16x16x32_bf16 v[94:97], v[156:159], v[204:207], v[94:97]
	v_mfma_f32_16x16x32_bf16 v[94:97], v[160:163], v[208:211], v[94:97]
	v_mfma_f32_16x16x32_bf16 v[90:93], v[168:171], v[208:211], v[90:93]
	v_mfma_f32_16x16x32_bf16 v[90:93], v[164:167], v[204:207], v[90:93]
	v_mfma_f32_16x16x32_bf16 v[74:77], v[164:167], v[214:217], v[74:77]
	v_mfma_f32_16x16x32_bf16 v[74:77], v[168:171], v[218:221], v[74:77]
	v_mfma_f32_16x16x32_bf16 v[78:81], v[160:163], v[218:221], v[78:81]
	v_mfma_f32_16x16x32_bf16 v[78:81], v[156:159], v[214:217], v[78:81]
	v_mfma_f32_16x16x32_bf16 v[118:121], v[172:175], v[188:191], v[118:121]
	v_mfma_f32_16x16x32_bf16 v[118:121], v[176:179], v[192:195], v[118:121]
	v_mfma_f32_16x16x32_bf16 v[114:117], v[184:187], v[192:195], v[114:117]
	v_mfma_f32_16x16x32_bf16 v[114:117], v[180:183], v[188:191], v[114:117]
	v_mfma_f32_16x16x32_bf16 v[98:101], v[180:183], v[196:199], v[98:101]
	v_mfma_f32_16x16x32_bf16 v[98:101], v[184:187], v[200:203], v[98:101]
	v_mfma_f32_16x16x32_bf16 v[102:105], v[176:179], v[200:203], v[102:105]
	v_mfma_f32_16x16x32_bf16 v[102:105], v[172:175], v[196:199], v[102:105]
	v_mfma_f32_16x16x32_bf16 v[86:89], v[172:175], v[204:207], v[86:89]
	v_mfma_f32_16x16x32_bf16 v[86:89], v[176:179], v[208:211], v[86:89]
	v_mfma_f32_16x16x32_bf16 v[82:85], v[184:187], v[208:211], v[82:85]
	v_mfma_f32_16x16x32_bf16 v[82:85], v[180:183], v[204:207], v[82:85]
	v_mfma_f32_16x16x32_bf16 v[66:69], v[180:183], v[214:217], v[66:69]
	v_mfma_f32_16x16x32_bf16 v[66:69], v[184:187], v[218:221], v[66:69]
	v_mfma_f32_16x16x32_bf16 v[70:73], v[176:179], v[218:221], v[70:73]
	v_mfma_f32_16x16x32_bf16 v[70:73], v[172:175], v[214:217], v[70:73]
	s_barrier
	s_mov_b32 m0, s48
	s_add_u32 s66, s38, 0x108000
	ds_read_b128 v[188:191], v152 offset:16384
	ds_read_b128 v[192:195], v152 offset:17408
	ds_read_b128 v[196:199], v152 offset:18432
	ds_read_b128 v[200:203], v152 offset:19456
	ds_read_b128 v[204:207], v152 offset:20480
	ds_read_b128 v[208:211], v152 offset:21504
	ds_read_b128 v[214:217], v152 offset:22528
	ds_read_b128 v[218:221], v152 offset:23552
	global_load_lds_dwordx4 v132, s[38:39]
	s_mov_b32 m0, s49
	s_addc_u32 s67, s39, 0
	global_load_lds_dwordx4 v136, s[38:39]
	s_mov_b32 m0, s50
	s_nop 0
	global_load_lds_dwordx4 v132, s[66:67]
	s_mov_b32 m0, s51
	s_nop 0
	global_load_lds_dwordx4 v136, s[66:67]
	s_mov_b32 m0, s3
	s_nop 0
	global_load_lds_dwordx4 v130, s[40:41]
	s_mov_b32 m0, s33
	s_nop 0
	global_load_lds_dwordx4 v134, s[40:41]
	s_waitcnt vmcnt(8)
	s_waitcnt lgkmcnt(0)
	s_barrier
	s_waitcnt lgkmcnt(0)
	v_mfma_f32_16x16x32_bf16 v[62:65], v[156:159], v[188:191], v[62:65]
	v_mfma_f32_16x16x32_bf16 v[62:65], v[160:163], v[192:195], v[62:65]
	v_mfma_f32_16x16x32_bf16 v[58:61], v[168:171], v[192:195], v[58:61]
	v_mfma_f32_16x16x32_bf16 v[58:61], v[164:167], v[188:191], v[58:61]
	v_mfma_f32_16x16x32_bf16 v[42:45], v[164:167], v[196:199], v[42:45]
	v_mfma_f32_16x16x32_bf16 v[42:45], v[168:171], v[200:203], v[42:45]
	v_mfma_f32_16x16x32_bf16 v[46:49], v[160:163], v[200:203], v[46:49]
	v_mfma_f32_16x16x32_bf16 v[46:49], v[156:159], v[196:199], v[46:49]
	v_mfma_f32_16x16x32_bf16 v[30:33], v[156:159], v[204:207], v[30:33]
	v_mfma_f32_16x16x32_bf16 v[30:33], v[160:163], v[208:211], v[30:33]
	v_mfma_f32_16x16x32_bf16 v[26:29], v[168:171], v[208:211], v[26:29]
	v_mfma_f32_16x16x32_bf16 v[26:29], v[164:167], v[204:207], v[26:29]
	v_mfma_f32_16x16x32_bf16 v[10:13], v[164:167], v[214:217], v[10:13]
	v_mfma_f32_16x16x32_bf16 v[10:13], v[168:171], v[218:221], v[10:13]
	v_mfma_f32_16x16x32_bf16 v[14:17], v[160:163], v[218:221], v[14:17]
	v_mfma_f32_16x16x32_bf16 v[14:17], v[156:159], v[214:217], v[14:17]
	v_mfma_f32_16x16x32_bf16 v[54:57], v[172:175], v[188:191], v[54:57]
	v_mfma_f32_16x16x32_bf16 v[54:57], v[176:179], v[192:195], v[54:57]
	v_mfma_f32_16x16x32_bf16 v[50:53], v[184:187], v[192:195], v[50:53]
	v_mfma_f32_16x16x32_bf16 v[50:53], v[180:183], v[188:191], v[50:53]
	v_mfma_f32_16x16x32_bf16 v[34:37], v[180:183], v[196:199], v[34:37]
	v_mfma_f32_16x16x32_bf16 v[34:37], v[184:187], v[200:203], v[34:37]
	v_mfma_f32_16x16x32_bf16 v[38:41], v[176:179], v[200:203], v[38:41]
	v_mfma_f32_16x16x32_bf16 v[38:41], v[172:175], v[196:199], v[38:41]
	v_mfma_f32_16x16x32_bf16 v[22:25], v[172:175], v[204:207], v[22:25]
	v_mfma_f32_16x16x32_bf16 v[22:25], v[176:179], v[208:211], v[22:25]
	v_mfma_f32_16x16x32_bf16 v[18:21], v[184:187], v[208:211], v[18:21]
	v_mfma_f32_16x16x32_bf16 v[18:21], v[180:183], v[204:207], v[18:21]
	v_mfma_f32_16x16x32_bf16 v[2:5], v[180:183], v[214:217], v[2:5]
	v_mfma_f32_16x16x32_bf16 v[2:5], v[184:187], v[218:221], v[2:5]
	v_mfma_f32_16x16x32_bf16 v[6:9], v[176:179], v[218:221], v[6:9]
	v_mfma_f32_16x16x32_bf16 v[6:9], v[172:175], v[214:217], v[6:9]
	s_barrier
	ds_read_b128 v[156:159], v153
	ds_read_b128 v[160:163], v153 offset:1024
	ds_read_b128 v[164:167], v153 offset:2048
	ds_read_b128 v[168:171], v153 offset:3072
	ds_read_b128 v[172:175], v154
	ds_read_b128 v[176:179], v154 offset:1024
	ds_read_b128 v[180:183], v154 offset:2048
	ds_read_b128 v[184:187], v154 offset:3072
	s_add_u32 s40, s40, 0x108000
	s_addc_u32 s41, s41, 0
	s_mov_b32 m0, s42
	ds_read_b128 v[188:191], v152 offset:32768
	ds_read_b128 v[192:195], v152 offset:33792
	ds_read_b128 v[196:199], v152 offset:34816
	ds_read_b128 v[200:203], v152 offset:35840
	ds_read_b128 v[204:207], v152 offset:36864
	ds_read_b128 v[208:211], v152 offset:37888
	ds_read_b128 v[214:217], v152 offset:38912
	ds_read_b128 v[218:221], v152 offset:39936
	global_load_lds_dwordx4 v130, s[40:41]
	s_mov_b32 m0, s43
	s_nop 0
	global_load_lds_dwordx4 v134, s[40:41]
	s_waitcnt vmcnt(8)
	s_waitcnt lgkmcnt(0)
	s_barrier
	s_waitcnt lgkmcnt(0)
	v_mfma_f32_16x16x32_bf16 v[126:129], v[156:159], v[188:191], v[126:129]
	v_mfma_f32_16x16x32_bf16 v[126:129], v[160:163], v[192:195], v[126:129]
	v_mfma_f32_16x16x32_bf16 v[122:125], v[168:171], v[192:195], v[122:125]
	v_mfma_f32_16x16x32_bf16 v[122:125], v[164:167], v[188:191], v[122:125]
	v_mfma_f32_16x16x32_bf16 v[106:109], v[164:167], v[196:199], v[106:109]
	v_mfma_f32_16x16x32_bf16 v[106:109], v[168:171], v[200:203], v[106:109]
	v_mfma_f32_16x16x32_bf16 v[110:113], v[160:163], v[200:203], v[110:113]
	v_mfma_f32_16x16x32_bf16 v[110:113], v[156:159], v[196:199], v[110:113]
	v_mfma_f32_16x16x32_bf16 v[94:97], v[156:159], v[204:207], v[94:97]
	v_mfma_f32_16x16x32_bf16 v[94:97], v[160:163], v[208:211], v[94:97]
	v_mfma_f32_16x16x32_bf16 v[90:93], v[168:171], v[208:211], v[90:93]
	v_mfma_f32_16x16x32_bf16 v[90:93], v[164:167], v[204:207], v[90:93]
	v_mfma_f32_16x16x32_bf16 v[74:77], v[164:167], v[214:217], v[74:77]
	v_mfma_f32_16x16x32_bf16 v[74:77], v[168:171], v[218:221], v[74:77]
	v_mfma_f32_16x16x32_bf16 v[78:81], v[160:163], v[218:221], v[78:81]
	v_mfma_f32_16x16x32_bf16 v[78:81], v[156:159], v[214:217], v[78:81]
	v_mfma_f32_16x16x32_bf16 v[118:121], v[172:175], v[188:191], v[118:121]
	v_mfma_f32_16x16x32_bf16 v[118:121], v[176:179], v[192:195], v[118:121]
	v_mfma_f32_16x16x32_bf16 v[114:117], v[184:187], v[192:195], v[114:117]
	v_mfma_f32_16x16x32_bf16 v[114:117], v[180:183], v[188:191], v[114:117]
	v_mfma_f32_16x16x32_bf16 v[98:101], v[180:183], v[196:199], v[98:101]
	v_mfma_f32_16x16x32_bf16 v[98:101], v[184:187], v[200:203], v[98:101]
	v_mfma_f32_16x16x32_bf16 v[102:105], v[176:179], v[200:203], v[102:105]
	v_mfma_f32_16x16x32_bf16 v[102:105], v[172:175], v[196:199], v[102:105]
	v_mfma_f32_16x16x32_bf16 v[86:89], v[172:175], v[204:207], v[86:89]
	v_mfma_f32_16x16x32_bf16 v[86:89], v[176:179], v[208:211], v[86:89]
	v_mfma_f32_16x16x32_bf16 v[82:85], v[184:187], v[208:211], v[82:85]
	v_mfma_f32_16x16x32_bf16 v[82:85], v[180:183], v[204:207], v[82:85]
	v_mfma_f32_16x16x32_bf16 v[66:69], v[180:183], v[214:217], v[66:69]
	v_mfma_f32_16x16x32_bf16 v[66:69], v[184:187], v[218:221], v[66:69]
	v_mfma_f32_16x16x32_bf16 v[70:73], v[176:179], v[218:221], v[70:73]
	v_mfma_f32_16x16x32_bf16 v[70:73], v[172:175], v[214:217], v[70:73]
	s_barrier
	s_mov_b32 m0, s53
	s_add_u32 s38, s38, 0x80
	s_addc_u32 s39, s39, 0
	ds_read_b128 v[188:191], v152 offset:49152
	ds_read_b128 v[192:195], v152 offset:50176
	ds_read_b128 v[196:199], v152 offset:51200
	ds_read_b128 v[200:203], v152 offset:52224
	ds_read_b128 v[204:207], v152 offset:53248
	ds_read_b128 v[208:211], v152 offset:54272
	ds_read_b128 v[214:217], v152 offset:55296
	ds_read_b128 v[218:221], v152 offset:56320
	global_load_lds_dwordx4 v132, s[38:39]
	s_mov_b32 m0, s54
	s_add_i32 s40, s52, s2
	global_load_lds_dwordx4 v136, s[38:39]
	s_add_u32 s38, s38, 0x108000
	s_addc_u32 s39, s39, 0
	s_mov_b32 m0, s40
	s_nop 0
	global_load_lds_dwordx4 v132, s[38:39]
	s_add_i32 m0, s40, 0x2000
	s_nop 0
	global_load_lds_dwordx4 v136, s[38:39]
	s_mov_b32 m0, s44
	s_nop 0
	global_load_lds_dwordx4 v130, s[36:37]
	s_mov_b32 m0, s45
	s_nop 0
	global_load_lds_dwordx4 v134, s[36:37]
	s_waitcnt vmcnt(8)
	s_waitcnt lgkmcnt(0)
	s_barrier
	s_waitcnt lgkmcnt(0)
	v_mfma_f32_16x16x32_bf16 v[62:65], v[156:159], v[188:191], v[62:65]
	v_mfma_f32_16x16x32_bf16 v[62:65], v[160:163], v[192:195], v[62:65]
	v_mfma_f32_16x16x32_bf16 v[58:61], v[168:171], v[192:195], v[58:61]
	v_mfma_f32_16x16x32_bf16 v[58:61], v[164:167], v[188:191], v[58:61]
	v_mfma_f32_16x16x32_bf16 v[42:45], v[164:167], v[196:199], v[42:45]
	v_mfma_f32_16x16x32_bf16 v[42:45], v[168:171], v[200:203], v[42:45]
	v_mfma_f32_16x16x32_bf16 v[46:49], v[160:163], v[200:203], v[46:49]
	v_mfma_f32_16x16x32_bf16 v[46:49], v[156:159], v[196:199], v[46:49]
	v_mfma_f32_16x16x32_bf16 v[30:33], v[156:159], v[204:207], v[30:33]
	v_mfma_f32_16x16x32_bf16 v[30:33], v[160:163], v[208:211], v[30:33]
	v_mfma_f32_16x16x32_bf16 v[26:29], v[168:171], v[208:211], v[26:29]
	v_mfma_f32_16x16x32_bf16 v[26:29], v[164:167], v[204:207], v[26:29]
	v_mfma_f32_16x16x32_bf16 v[10:13], v[164:167], v[214:217], v[10:13]
	v_mfma_f32_16x16x32_bf16 v[10:13], v[168:171], v[218:221], v[10:13]
	v_mfma_f32_16x16x32_bf16 v[14:17], v[160:163], v[218:221], v[14:17]
	v_mfma_f32_16x16x32_bf16 v[14:17], v[156:159], v[214:217], v[14:17]
	v_mfma_f32_16x16x32_bf16 v[54:57], v[172:175], v[188:191], v[54:57]
	v_mfma_f32_16x16x32_bf16 v[54:57], v[176:179], v[192:195], v[54:57]
	v_mfma_f32_16x16x32_bf16 v[50:53], v[184:187], v[192:195], v[50:53]
	v_mfma_f32_16x16x32_bf16 v[50:53], v[180:183], v[188:191], v[50:53]
	v_mfma_f32_16x16x32_bf16 v[34:37], v[180:183], v[196:199], v[34:37]
	v_mfma_f32_16x16x32_bf16 v[34:37], v[184:187], v[200:203], v[34:37]
	v_mfma_f32_16x16x32_bf16 v[38:41], v[176:179], v[200:203], v[38:41]
	v_mfma_f32_16x16x32_bf16 v[38:41], v[172:175], v[196:199], v[38:41]
	v_mfma_f32_16x16x32_bf16 v[22:25], v[172:175], v[204:207], v[22:25]
	v_mfma_f32_16x16x32_bf16 v[22:25], v[176:179], v[208:211], v[22:25]
	v_mfma_f32_16x16x32_bf16 v[18:21], v[184:187], v[208:211], v[18:21]
	v_mfma_f32_16x16x32_bf16 v[18:21], v[180:183], v[204:207], v[18:21]
	v_mfma_f32_16x16x32_bf16 v[2:5], v[180:183], v[214:217], v[2:5]
	v_mfma_f32_16x16x32_bf16 v[2:5], v[184:187], v[218:221], v[2:5]
	v_mfma_f32_16x16x32_bf16 v[6:9], v[176:179], v[218:221], v[6:9]
	v_mfma_f32_16x16x32_bf16 v[6:9], v[172:175], v[214:217], v[6:9]
	s_barrier
	s_add_i32 s64, s64, 2
	s_add_u32 s34, s34, 0x100
	s_addc_u32 s35, s35, 0
	s_cmp_gt_u32 s64, 61
	s_cbranch_scc0 .LBB0_235
	s_and_b64 vcc, exec, s[20:21]
	s_cbranch_vccz .LBB0_238
	s_barrier

.LBB0_434:
	ds_read_b128 v[134:137], v204
	ds_read_b128 v[138:141], v204 offset:1024
	ds_read_b128 v[142:145], v204 offset:2048
	ds_read_b128 v[146:149], v204 offset:3072
	ds_read_b128 v[150:153], v205
	ds_read_b128 v[154:157], v205 offset:1024
	ds_read_b128 v[158:161], v205 offset:2048
	ds_read_b128 v[162:165], v205 offset:3072
	s_add_u32 s34, s22, s30
	s_addc_u32 s35, s23, s31
	s_add_u32 s38, s34, 0x100
	s_addc_u32 s39, s35, 0
	s_add_u32 s36, s60, s30
	s_addc_u32 s37, s61, s31
	s_add_u32 s34, s34, 0x180
	s_addc_u32 s35, s35, 0
	s_cmpk_eq_i32 s30, 0xb00
	s_cselect_b32 s35, s59, s35
	s_cselect_b32 s34, s58, s34
	s_cselect_b32 s37, s21, s37
	s_cselect_b32 s36, s20, s36
	s_cselect_b32 s39, s17, s39
	s_cselect_b32 s38, s16, s38
	v_lshl_add_u64 v[200:201], v[130:131], 0, s[30:31]
	s_add_i32 m0, s3, 0xc000
	ds_read_b128 v[166:169], v206
	ds_read_b128 v[170:173], v206 offset:1024
	ds_read_b128 v[174:177], v206 offset:2048
	ds_read_b128 v[178:181], v206 offset:3072
	ds_read_b128 v[182:185], v206 offset:4096
	ds_read_b128 v[208:211], v206 offset:5120
	ds_read_b128 v[214:217], v206 offset:6144
	ds_read_b128 v[218:221], v206 offset:7168
	global_load_lds_dwordx4 v[200:201], off
	v_lshl_add_u64 v[200:201], v[132:133], 0, s[30:31]
	s_add_i32 m0, s3, 0xe000
	s_nop 0
	global_load_lds_dwordx4 v[200:201], off
	s_waitcnt vmcnt(8)
	s_waitcnt lgkmcnt(0)
	s_barrier
	s_waitcnt lgkmcnt(0)
	v_mfma_f32_16x16x32_bf16 v[126:129], v[134:137], v[166:169], v[126:129]
	v_mfma_f32_16x16x32_bf16 v[126:129], v[138:141], v[170:173], v[126:129]
	v_mfma_f32_16x16x32_bf16 v[122:125], v[146:149], v[170:173], v[122:125]
	v_mfma_f32_16x16x32_bf16 v[122:125], v[142:145], v[166:169], v[122:125]
	v_mfma_f32_16x16x32_bf16 v[106:109], v[142:145], v[174:177], v[106:109]
	v_mfma_f32_16x16x32_bf16 v[106:109], v[146:149], v[178:181], v[106:109]
	v_mfma_f32_16x16x32_bf16 v[110:113], v[138:141], v[178:181], v[110:113]
	v_mfma_f32_16x16x32_bf16 v[110:113], v[134:137], v[174:177], v[110:113]
	v_mfma_f32_16x16x32_bf16 v[94:97], v[134:137], v[182:185], v[94:97]
	v_mfma_f32_16x16x32_bf16 v[94:97], v[138:141], v[208:211], v[94:97]
	v_mfma_f32_16x16x32_bf16 v[90:93], v[146:149], v[208:211], v[90:93]
	v_mfma_f32_16x16x32_bf16 v[90:93], v[142:145], v[182:185], v[90:93]
	v_mfma_f32_16x16x32_bf16 v[74:77], v[142:145], v[214:217], v[74:77]
	v_mfma_f32_16x16x32_bf16 v[74:77], v[146:149], v[218:221], v[74:77]
	v_mfma_f32_16x16x32_bf16 v[78:81], v[138:141], v[218:221], v[78:81]
	v_mfma_f32_16x16x32_bf16 v[78:81], v[134:137], v[214:217], v[78:81]
	v_mfma_f32_16x16x32_bf16 v[118:121], v[150:153], v[166:169], v[118:121]
	v_mfma_f32_16x16x32_bf16 v[118:121], v[154:157], v[170:173], v[118:121]
	v_mfma_f32_16x16x32_bf16 v[114:117], v[162:165], v[170:173], v[114:117]
	v_mfma_f32_16x16x32_bf16 v[114:117], v[158:161], v[166:169], v[114:117]
	v_mfma_f32_16x16x32_bf16 v[98:101], v[158:161], v[174:177], v[98:101]
	v_mfma_f32_16x16x32_bf16 v[98:101], v[162:165], v[178:181], v[98:101]
	v_mfma_f32_16x16x32_bf16 v[102:105], v[154:157], v[178:181], v[102:105]
	v_mfma_f32_16x16x32_bf16 v[102:105], v[150:153], v[174:177], v[102:105]
	v_mfma_f32_16x16x32_bf16 v[86:89], v[150:153], v[182:185], v[86:89]
	v_mfma_f32_16x16x32_bf16 v[86:89], v[154:157], v[208:211], v[86:89]
	v_mfma_f32_16x16x32_bf16 v[82:85], v[162:165], v[208:211], v[82:85]
	v_mfma_f32_16x16x32_bf16 v[82:85], v[158:161], v[182:185], v[82:85]
	v_mfma_f32_16x16x32_bf16 v[66:69], v[158:161], v[214:217], v[66:69]
	v_mfma_f32_16x16x32_bf16 v[66:69], v[162:165], v[218:221], v[66:69]
	v_mfma_f32_16x16x32_bf16 v[70:73], v[154:157], v[218:221], v[70:73]
	v_mfma_f32_16x16x32_bf16 v[70:73], v[150:153], v[214:217], v[70:73]
	s_barrier
	s_add_i32 s63, s52, s2
	s_mov_b32 m0, s63
	ds_read_b128 v[166:169], v206 offset:16384
	ds_read_b128 v[170:173], v206 offset:17408
	ds_read_b128 v[174:177], v206 offset:18432
	ds_read_b128 v[178:181], v206 offset:19456
	ds_read_b128 v[182:185], v206 offset:20480
	ds_read_b128 v[208:211], v206 offset:21504
	ds_read_b128 v[214:217], v206 offset:22528
	ds_read_b128 v[218:221], v206 offset:23552
	global_load_lds_dwordx4 v188, s[36:37]
	s_add_i32 m0, s63, 0x2000
	s_add_u32 s64, s36, 0x68000
	s_addc_u32 s65, s37, 0
	s_add_i32 s63, s53, s2
	global_load_lds_dwordx4 v192, s[36:37]
	s_mov_b32 m0, s63
	s_nop 0
	global_load_lds_dwordx4 v188, s[64:65]
	s_add_i32 m0, s63, 0x2000
	s_nop 0
	global_load_lds_dwordx4 v192, s[64:65]
	s_mov_b32 m0, s3
	s_nop 0
	global_load_lds_dwordx4 v186, s[38:39]
	s_mov_b32 m0, s33
	s_nop 0
	global_load_lds_dwordx4 v190, s[38:39]
	s_waitcnt vmcnt(8)
	s_waitcnt lgkmcnt(0)
	s_barrier
	s_waitcnt lgkmcnt(0)
	v_mfma_f32_16x16x32_bf16 v[62:65], v[134:137], v[166:169], v[62:65]
	v_mfma_f32_16x16x32_bf16 v[62:65], v[138:141], v[170:173], v[62:65]
	v_mfma_f32_16x16x32_bf16 v[58:61], v[146:149], v[170:173], v[58:61]
	v_mfma_f32_16x16x32_bf16 v[58:61], v[142:145], v[166:169], v[58:61]
	v_mfma_f32_16x16x32_bf16 v[42:45], v[142:145], v[174:177], v[42:45]
	v_mfma_f32_16x16x32_bf16 v[42:45], v[146:149], v[178:181], v[42:45]
	v_mfma_f32_16x16x32_bf16 v[46:49], v[138:141], v[178:181], v[46:49]
	v_mfma_f32_16x16x32_bf16 v[46:49], v[134:137], v[174:177], v[46:49]
	v_mfma_f32_16x16x32_bf16 v[30:33], v[134:137], v[182:185], v[30:33]
	v_mfma_f32_16x16x32_bf16 v[30:33], v[138:141], v[208:211], v[30:33]
	v_mfma_f32_16x16x32_bf16 v[26:29], v[146:149], v[208:211], v[26:29]
	v_mfma_f32_16x16x32_bf16 v[26:29], v[142:145], v[182:185], v[26:29]
	v_mfma_f32_16x16x32_bf16 v[10:13], v[142:145], v[214:217], v[10:13]
	v_mfma_f32_16x16x32_bf16 v[10:13], v[146:149], v[218:221], v[10:13]
	v_mfma_f32_16x16x32_bf16 v[14:17], v[138:141], v[218:221], v[14:17]
	v_mfma_f32_16x16x32_bf16 v[14:17], v[134:137], v[214:217], v[14:17]
	v_mfma_f32_16x16x32_bf16 v[54:57], v[150:153], v[166:169], v[54:57]
	v_mfma_f32_16x16x32_bf16 v[54:57], v[154:157], v[170:173], v[54:57]
	v_mfma_f32_16x16x32_bf16 v[50:53], v[162:165], v[170:173], v[50:53]
	v_mfma_f32_16x16x32_bf16 v[50:53], v[158:161], v[166:169], v[50:53]
	v_mfma_f32_16x16x32_bf16 v[34:37], v[158:161], v[174:177], v[34:37]
	v_mfma_f32_16x16x32_bf16 v[34:37], v[162:165], v[178:181], v[34:37]
	v_mfma_f32_16x16x32_bf16 v[38:41], v[154:157], v[178:181], v[38:41]
	v_mfma_f32_16x16x32_bf16 v[38:41], v[150:153], v[174:177], v[38:41]
	v_mfma_f32_16x16x32_bf16 v[22:25], v[150:153], v[182:185], v[22:25]
	v_mfma_f32_16x16x32_bf16 v[22:25], v[154:157], v[208:211], v[22:25]
	v_mfma_f32_16x16x32_bf16 v[18:21], v[162:165], v[208:211], v[18:21]
	v_mfma_f32_16x16x32_bf16 v[18:21], v[158:161], v[182:185], v[18:21]
	v_mfma_f32_16x16x32_bf16 v[2:5], v[158:161], v[214:217], v[2:5]
	v_mfma_f32_16x16x32_bf16 v[2:5], v[162:165], v[218:221], v[2:5]
	v_mfma_f32_16x16x32_bf16 v[6:9], v[154:157], v[218:221], v[6:9]
	v_mfma_f32_16x16x32_bf16 v[6:9], v[150:153], v[214:217], v[6:9]
	s_barrier
	s_add_i32 s63, 0, 0x18000
	s_add_i32 s64, 0, 0x1c000
	v_add_u32_e32 v146, s63, v202
	v_add_u32_e32 v162, s64, v202
	ds_read_b128 v[134:137], v146
	ds_read_b128 v[138:141], v146 offset:1024
	ds_read_b128 v[142:145], v146 offset:2048
	ds_read_b128 v[146:149], v146 offset:3072
	ds_read_b128 v[150:153], v162
	ds_read_b128 v[154:157], v162 offset:1024
	ds_read_b128 v[158:161], v162 offset:2048
	ds_read_b128 v[162:165], v162 offset:3072
	s_add_u32 s38, s38, 0x188000
	s_addc_u32 s39, s39, 0
	s_mov_b32 m0, s40
	ds_read_b128 v[166:169], v206 offset:32768
	ds_read_b128 v[170:173], v206 offset:33792
	ds_read_b128 v[174:177], v206 offset:34816
	ds_read_b128 v[178:181], v206 offset:35840
	ds_read_b128 v[182:185], v206 offset:36864
	ds_read_b128 v[208:211], v206 offset:37888
	ds_read_b128 v[214:217], v206 offset:38912
	ds_read_b128 v[218:221], v206 offset:39936
	global_load_lds_dwordx4 v186, s[38:39]
	s_mov_b32 m0, s41
	s_nop 0
	global_load_lds_dwordx4 v190, s[38:39]
	s_waitcnt vmcnt(8)
	s_waitcnt lgkmcnt(0)
	s_barrier
	s_waitcnt lgkmcnt(0)
	v_mfma_f32_16x16x32_bf16 v[126:129], v[134:137], v[166:169], v[126:129]
	v_mfma_f32_16x16x32_bf16 v[126:129], v[138:141], v[170:173], v[126:129]
	v_mfma_f32_16x16x32_bf16 v[122:125], v[146:149], v[170:173], v[122:125]
	v_mfma_f32_16x16x32_bf16 v[122:125], v[142:145], v[166:169], v[122:125]
	v_mfma_f32_16x16x32_bf16 v[106:109], v[142:145], v[174:177], v[106:109]
	v_mfma_f32_16x16x32_bf16 v[106:109], v[146:149], v[178:181], v[106:109]
	v_mfma_f32_16x16x32_bf16 v[110:113], v[138:141], v[178:181], v[110:113]
	v_mfma_f32_16x16x32_bf16 v[110:113], v[134:137], v[174:177], v[110:113]
	v_mfma_f32_16x16x32_bf16 v[94:97], v[134:137], v[182:185], v[94:97]
	v_mfma_f32_16x16x32_bf16 v[94:97], v[138:141], v[208:211], v[94:97]
	v_mfma_f32_16x16x32_bf16 v[90:93], v[146:149], v[208:211], v[90:93]
	v_mfma_f32_16x16x32_bf16 v[90:93], v[142:145], v[182:185], v[90:93]
	v_mfma_f32_16x16x32_bf16 v[74:77], v[142:145], v[214:217], v[74:77]
	v_mfma_f32_16x16x32_bf16 v[74:77], v[146:149], v[218:221], v[74:77]
	v_mfma_f32_16x16x32_bf16 v[78:81], v[138:141], v[218:221], v[78:81]
	v_mfma_f32_16x16x32_bf16 v[78:81], v[134:137], v[214:217], v[78:81]
	v_mfma_f32_16x16x32_bf16 v[118:121], v[150:153], v[166:169], v[118:121]
	v_mfma_f32_16x16x32_bf16 v[118:121], v[154:157], v[170:173], v[118:121]
	v_mfma_f32_16x16x32_bf16 v[114:117], v[162:165], v[170:173], v[114:117]
	v_mfma_f32_16x16x32_bf16 v[114:117], v[158:161], v[166:169], v[114:117]
	v_mfma_f32_16x16x32_bf16 v[98:101], v[158:161], v[174:177], v[98:101]
	v_mfma_f32_16x16x32_bf16 v[98:101], v[162:165], v[178:181], v[98:101]
	v_mfma_f32_16x16x32_bf16 v[102:105], v[154:157], v[178:181], v[102:105]
	v_mfma_f32_16x16x32_bf16 v[102:105], v[150:153], v[174:177], v[102:105]
	v_mfma_f32_16x16x32_bf16 v[86:89], v[150:153], v[182:185], v[86:89]
	v_mfma_f32_16x16x32_bf16 v[86:89], v[154:157], v[208:211], v[86:89]
	v_mfma_f32_16x16x32_bf16 v[82:85], v[162:165], v[208:211], v[82:85]
	v_mfma_f32_16x16x32_bf16 v[82:85], v[158:161], v[182:185], v[82:85]
	v_mfma_f32_16x16x32_bf16 v[66:69], v[158:161], v[214:217], v[66:69]
	v_mfma_f32_16x16x32_bf16 v[66:69], v[162:165], v[218:221], v[66:69]
	v_mfma_f32_16x16x32_bf16 v[70:73], v[154:157], v[218:221], v[70:73]
	v_mfma_f32_16x16x32_bf16 v[70:73], v[150:153], v[214:217], v[70:73]
	s_barrier
	s_add_i32 s38, s63, s2
	s_add_u32 s36, s36, 0x80
	s_addc_u32 s37, s37, 0
	s_mov_b32 m0, s38
	ds_read_b128 v[166:169], v206 offset:49152
	ds_read_b128 v[170:173], v206 offset:50176
	ds_read_b128 v[174:177], v206 offset:51200
	ds_read_b128 v[178:181], v206 offset:52224
	ds_read_b128 v[182:185], v206 offset:53248
	ds_read_b128 v[208:211], v206 offset:54272
	ds_read_b128 v[214:217], v206 offset:55296
	ds_read_b128 v[218:221], v206 offset:56320
	global_load_lds_dwordx4 v188, s[36:37]
	s_add_i32 m0, s38, 0x2000
	s_add_i32 s38, s64, s2
	global_load_lds_dwordx4 v192, s[36:37]
	s_add_u32 s36, s36, 0x68000
	s_addc_u32 s37, s37, 0
	s_mov_b32 m0, s38
	s_nop 0
	global_load_lds_dwordx4 v188, s[36:37]
	s_add_i32 m0, s38, 0x2000
	s_nop 0
	global_load_lds_dwordx4 v192, s[36:37]
	s_mov_b32 m0, s50
	s_nop 0
	global_load_lds_dwordx4 v186, s[34:35]
	s_mov_b32 m0, s51
	s_nop 0
	global_load_lds_dwordx4 v190, s[34:35]
	s_waitcnt vmcnt(8)
	s_waitcnt lgkmcnt(0)
	s_barrier
	s_waitcnt lgkmcnt(0)
	v_mfma_f32_16x16x32_bf16 v[62:65], v[134:137], v[166:169], v[62:65]
	v_mfma_f32_16x16x32_bf16 v[62:65], v[138:141], v[170:173], v[62:65]
	v_mfma_f32_16x16x32_bf16 v[58:61], v[146:149], v[170:173], v[58:61]
	v_mfma_f32_16x16x32_bf16 v[58:61], v[142:145], v[166:169], v[58:61]
	v_mfma_f32_16x16x32_bf16 v[42:45], v[142:145], v[174:177], v[42:45]
	v_mfma_f32_16x16x32_bf16 v[42:45], v[146:149], v[178:181], v[42:45]
	v_mfma_f32_16x16x32_bf16 v[46:49], v[138:141], v[178:181], v[46:49]
	v_mfma_f32_16x16x32_bf16 v[46:49], v[134:137], v[174:177], v[46:49]
	v_mfma_f32_16x16x32_bf16 v[30:33], v[134:137], v[182:185], v[30:33]
	v_mfma_f32_16x16x32_bf16 v[30:33], v[138:141], v[208:211], v[30:33]
	v_mfma_f32_16x16x32_bf16 v[26:29], v[146:149], v[208:211], v[26:29]
	v_mfma_f32_16x16x32_bf16 v[26:29], v[142:145], v[182:185], v[26:29]
	v_mfma_f32_16x16x32_bf16 v[10:13], v[142:145], v[214:217], v[10:13]
	v_mfma_f32_16x16x32_bf16 v[10:13], v[146:149], v[218:221], v[10:13]
	v_mfma_f32_16x16x32_bf16 v[14:17], v[138:141], v[218:221], v[14:17]
	v_mfma_f32_16x16x32_bf16 v[14:17], v[134:137], v[214:217], v[14:17]
	v_mfma_f32_16x16x32_bf16 v[54:57], v[150:153], v[166:169], v[54:57]
	v_mfma_f32_16x16x32_bf16 v[54:57], v[154:157], v[170:173], v[54:57]
	v_mfma_f32_16x16x32_bf16 v[50:53], v[162:165], v[170:173], v[50:53]
	v_mfma_f32_16x16x32_bf16 v[50:53], v[158:161], v[166:169], v[50:53]
	v_mfma_f32_16x16x32_bf16 v[34:37], v[158:161], v[174:177], v[34:37]
	v_mfma_f32_16x16x32_bf16 v[34:37], v[162:165], v[178:181], v[34:37]
	v_mfma_f32_16x16x32_bf16 v[38:41], v[154:157], v[178:181], v[38:41]
	v_mfma_f32_16x16x32_bf16 v[38:41], v[150:153], v[174:177], v[38:41]
	v_mfma_f32_16x16x32_bf16 v[22:25], v[150:153], v[182:185], v[22:25]
	v_mfma_f32_16x16x32_bf16 v[22:25], v[154:157], v[208:211], v[22:25]
	v_mfma_f32_16x16x32_bf16 v[18:21], v[162:165], v[208:211], v[18:21]
	v_mfma_f32_16x16x32_bf16 v[18:21], v[158:161], v[182:185], v[18:21]
	v_mfma_f32_16x16x32_bf16 v[2:5], v[158:161], v[214:217], v[2:5]
	v_mfma_f32_16x16x32_bf16 v[2:5], v[162:165], v[218:221], v[2:5]
	v_mfma_f32_16x16x32_bf16 v[6:9], v[154:157], v[218:221], v[6:9]
	v_mfma_f32_16x16x32_bf16 v[6:9], v[150:153], v[214:217], v[6:9]
	s_barrier
	s_add_i32 s62, s62, 2
	s_add_u32 s30, s30, 0x100
	s_addc_u32 s31, s31, 0
	s_cmp_gt_u32 s62, 21
	s_cbranch_scc0 .LBB0_434
	s_and_b64 vcc, exec, s[14:15]
	s_cbranch_vccz .LBB0_437
	s_barrier

.LBB0_612:
	ds_read_b128 v[166:169], v152
	ds_read_b128 v[170:173], v152 offset:1024
	ds_read_b128 v[174:177], v152 offset:2048
	ds_read_b128 v[178:181], v152 offset:3072
	ds_read_b128 v[182:185], v153
	ds_read_b128 v[186:189], v153 offset:1024
	ds_read_b128 v[190:193], v153 offset:2048
	ds_read_b128 v[194:197], v153 offset:3072
	s_add_u32 s26, s4, s22
	s_addc_u32 s27, s5, s23
	s_add_u32 s30, s26, 0x100
	s_addc_u32 s31, s27, 0
	s_add_u32 s28, s52, s22
	s_addc_u32 s29, s53, s23
	s_add_u32 s26, s26, 0x180
	s_addc_u32 s27, s27, 0
	s_cmpk_eq_i32 s22, 0x1f00
	s_cselect_b32 s27, s51, s27
	s_cselect_b32 s26, s50, s26
	s_cselect_b32 s29, s21, s29
	s_cselect_b32 s28, s20, s28
	s_cselect_b32 s31, s19, s31
	s_cselect_b32 s30, s18, s30
	s_mov_b32 m0, s37
	v_lshl_add_u64 v[210:211], v[148:149], 0, s[22:23]
	ds_read_b128 v[198:201], v154
	ds_read_b128 v[202:205], v154 offset:1024
	ds_read_b128 v[206:209], v154 offset:2048
	ds_read_b128 v[214:217], v154 offset:3072
	ds_read_b128 v[218:221], v154 offset:4096
	ds_read_b128 v[222:225], v154 offset:5120
	ds_read_b128 v[226:229], v154 offset:6144
	ds_read_b128 v[230:233], v154 offset:7168
	global_load_lds_dwordx4 v[210:211], off
	v_lshl_add_u64 v[210:211], v[150:151], 0, s[22:23]
	s_mov_b32 m0, s38
	s_nop 0
	global_load_lds_dwordx4 v[210:211], off
	s_waitcnt vmcnt(8)
	s_waitcnt lgkmcnt(0)
	s_barrier
	s_waitcnt lgkmcnt(0)
	v_mfma_f32_16x16x32_bf16 v[126:129], v[166:169], v[198:201], v[126:129]
	v_mfma_f32_16x16x32_bf16 v[126:129], v[170:173], v[202:205], v[126:129]
	v_mfma_f32_16x16x32_bf16 v[122:125], v[178:181], v[202:205], v[122:125]
	v_mfma_f32_16x16x32_bf16 v[122:125], v[174:177], v[198:201], v[122:125]
	v_mfma_f32_16x16x32_bf16 v[106:109], v[174:177], v[206:209], v[106:109]
	v_mfma_f32_16x16x32_bf16 v[106:109], v[178:181], v[214:217], v[106:109]
	v_mfma_f32_16x16x32_bf16 v[110:113], v[170:173], v[214:217], v[110:113]
	v_mfma_f32_16x16x32_bf16 v[110:113], v[166:169], v[206:209], v[110:113]
	v_mfma_f32_16x16x32_bf16 v[94:97], v[166:169], v[218:221], v[94:97]
	v_mfma_f32_16x16x32_bf16 v[94:97], v[170:173], v[222:225], v[94:97]
	v_mfma_f32_16x16x32_bf16 v[90:93], v[178:181], v[222:225], v[90:93]
	v_mfma_f32_16x16x32_bf16 v[90:93], v[174:177], v[218:221], v[90:93]
	v_mfma_f32_16x16x32_bf16 v[74:77], v[174:177], v[226:229], v[74:77]
	v_mfma_f32_16x16x32_bf16 v[74:77], v[178:181], v[230:233], v[74:77]
	v_mfma_f32_16x16x32_bf16 v[78:81], v[170:173], v[230:233], v[78:81]
	v_mfma_f32_16x16x32_bf16 v[78:81], v[166:169], v[226:229], v[78:81]
	v_mfma_f32_16x16x32_bf16 v[118:121], v[182:185], v[198:201], v[118:121]
	v_mfma_f32_16x16x32_bf16 v[118:121], v[186:189], v[202:205], v[118:121]
	v_mfma_f32_16x16x32_bf16 v[114:117], v[194:197], v[202:205], v[114:117]
	v_mfma_f32_16x16x32_bf16 v[114:117], v[190:193], v[198:201], v[114:117]
	v_mfma_f32_16x16x32_bf16 v[98:101], v[190:193], v[206:209], v[98:101]
	v_mfma_f32_16x16x32_bf16 v[98:101], v[194:197], v[214:217], v[98:101]
	v_mfma_f32_16x16x32_bf16 v[102:105], v[186:189], v[214:217], v[102:105]
	v_mfma_f32_16x16x32_bf16 v[102:105], v[182:185], v[206:209], v[102:105]
	v_mfma_f32_16x16x32_bf16 v[86:89], v[182:185], v[218:221], v[86:89]
	v_mfma_f32_16x16x32_bf16 v[86:89], v[186:189], v[222:225], v[86:89]
	v_mfma_f32_16x16x32_bf16 v[82:85], v[194:197], v[222:225], v[82:85]
	v_mfma_f32_16x16x32_bf16 v[82:85], v[190:193], v[218:221], v[82:85]
	v_mfma_f32_16x16x32_bf16 v[66:69], v[190:193], v[226:229], v[66:69]
	v_mfma_f32_16x16x32_bf16 v[66:69], v[194:197], v[230:233], v[66:69]
	v_mfma_f32_16x16x32_bf16 v[70:73], v[186:189], v[230:233], v[70:73]
	v_mfma_f32_16x16x32_bf16 v[70:73], v[182:185], v[226:229], v[70:73]
	s_barrier
	s_mov_b32 m0, s39
	s_add_u32 s56, s28, 0x108000
	ds_read_b128 v[198:201], v154 offset:16384
	ds_read_b128 v[202:205], v154 offset:17408
	ds_read_b128 v[206:209], v154 offset:18432
	ds_read_b128 v[214:217], v154 offset:19456
	ds_read_b128 v[218:221], v154 offset:20480
	ds_read_b128 v[222:225], v154 offset:21504
	ds_read_b128 v[226:229], v154 offset:22528
	ds_read_b128 v[230:233], v154 offset:23552
	global_load_lds_dwordx4 v132, s[28:29]
	s_mov_b32 m0, s40
	s_addc_u32 s57, s29, 0
	global_load_lds_dwordx4 v136, s[28:29]
	s_mov_b32 m0, s41
	s_nop 0
	global_load_lds_dwordx4 v132, s[56:57]
	s_mov_b32 m0, s42
	s_nop 0
	global_load_lds_dwordx4 v136, s[56:57]
	s_mov_b32 m0, s2
	s_nop 0
	global_load_lds_dwordx4 v130, s[30:31]
	s_mov_b32 m0, s3
	s_nop 0
	global_load_lds_dwordx4 v134, s[30:31]
	s_waitcnt vmcnt(8)
	s_waitcnt lgkmcnt(0)
	s_barrier
	s_waitcnt lgkmcnt(0)
	v_mfma_f32_16x16x32_bf16 v[62:65], v[166:169], v[198:201], v[62:65]
	v_mfma_f32_16x16x32_bf16 v[62:65], v[170:173], v[202:205], v[62:65]
	v_mfma_f32_16x16x32_bf16 v[58:61], v[178:181], v[202:205], v[58:61]
	v_mfma_f32_16x16x32_bf16 v[58:61], v[174:177], v[198:201], v[58:61]
	v_mfma_f32_16x16x32_bf16 v[42:45], v[174:177], v[206:209], v[42:45]
	v_mfma_f32_16x16x32_bf16 v[42:45], v[178:181], v[214:217], v[42:45]
	v_mfma_f32_16x16x32_bf16 v[46:49], v[170:173], v[214:217], v[46:49]
	v_mfma_f32_16x16x32_bf16 v[46:49], v[166:169], v[206:209], v[46:49]
	v_mfma_f32_16x16x32_bf16 v[30:33], v[166:169], v[218:221], v[30:33]
	v_mfma_f32_16x16x32_bf16 v[30:33], v[170:173], v[222:225], v[30:33]
	v_mfma_f32_16x16x32_bf16 v[26:29], v[178:181], v[222:225], v[26:29]
	v_mfma_f32_16x16x32_bf16 v[26:29], v[174:177], v[218:221], v[26:29]
	v_mfma_f32_16x16x32_bf16 v[10:13], v[174:177], v[226:229], v[10:13]
	v_mfma_f32_16x16x32_bf16 v[10:13], v[178:181], v[230:233], v[10:13]
	v_mfma_f32_16x16x32_bf16 v[14:17], v[170:173], v[230:233], v[14:17]
	v_mfma_f32_16x16x32_bf16 v[14:17], v[166:169], v[226:229], v[14:17]
	v_mfma_f32_16x16x32_bf16 v[54:57], v[182:185], v[198:201], v[54:57]
	v_mfma_f32_16x16x32_bf16 v[54:57], v[186:189], v[202:205], v[54:57]
	v_mfma_f32_16x16x32_bf16 v[50:53], v[194:197], v[202:205], v[50:53]
	v_mfma_f32_16x16x32_bf16 v[50:53], v[190:193], v[198:201], v[50:53]
	v_mfma_f32_16x16x32_bf16 v[34:37], v[190:193], v[206:209], v[34:37]
	v_mfma_f32_16x16x32_bf16 v[34:37], v[194:197], v[214:217], v[34:37]
	v_mfma_f32_16x16x32_bf16 v[38:41], v[186:189], v[214:217], v[38:41]
	v_mfma_f32_16x16x32_bf16 v[38:41], v[182:185], v[206:209], v[38:41]
	v_mfma_f32_16x16x32_bf16 v[22:25], v[182:185], v[218:221], v[22:25]
	v_mfma_f32_16x16x32_bf16 v[22:25], v[186:189], v[222:225], v[22:25]
	v_mfma_f32_16x16x32_bf16 v[18:21], v[194:197], v[222:225], v[18:21]
	v_mfma_f32_16x16x32_bf16 v[18:21], v[190:193], v[218:221], v[18:21]
	v_mfma_f32_16x16x32_bf16 v[2:5], v[190:193], v[226:229], v[2:5]
	v_mfma_f32_16x16x32_bf16 v[2:5], v[194:197], v[230:233], v[2:5]
	v_mfma_f32_16x16x32_bf16 v[6:9], v[186:189], v[230:233], v[6:9]
	v_mfma_f32_16x16x32_bf16 v[6:9], v[182:185], v[226:229], v[6:9]
	s_barrier
	ds_read_b128 v[166:169], v156
	ds_read_b128 v[170:173], v156 offset:1024
	ds_read_b128 v[174:177], v156 offset:2048
	ds_read_b128 v[178:181], v156 offset:3072
	ds_read_b128 v[182:185], v157
	ds_read_b128 v[186:189], v157 offset:1024
	ds_read_b128 v[190:193], v157 offset:2048
	ds_read_b128 v[194:197], v157 offset:3072
	s_add_u32 s30, s30, 0x108000
	s_addc_u32 s31, s31, 0
	s_mov_b32 m0, s33
	ds_read_b128 v[198:201], v154 offset:32768
	ds_read_b128 v[202:205], v154 offset:33792
	ds_read_b128 v[206:209], v154 offset:34816
	ds_read_b128 v[214:217], v154 offset:35840
	ds_read_b128 v[218:221], v154 offset:36864
	ds_read_b128 v[222:225], v154 offset:37888
	ds_read_b128 v[226:229], v154 offset:38912
	ds_read_b128 v[230:233], v154 offset:39936
	global_load_lds_dwordx4 v130, s[30:31]
	s_mov_b32 m0, s34
	s_nop 0
	global_load_lds_dwordx4 v134, s[30:31]
	s_waitcnt vmcnt(8)
	s_waitcnt lgkmcnt(0)
	s_barrier
	s_waitcnt lgkmcnt(0)
	v_mfma_f32_16x16x32_bf16 v[126:129], v[166:169], v[198:201], v[126:129]
	v_mfma_f32_16x16x32_bf16 v[126:129], v[170:173], v[202:205], v[126:129]
	v_mfma_f32_16x16x32_bf16 v[122:125], v[178:181], v[202:205], v[122:125]
	v_mfma_f32_16x16x32_bf16 v[122:125], v[174:177], v[198:201], v[122:125]
	v_mfma_f32_16x16x32_bf16 v[106:109], v[174:177], v[206:209], v[106:109]
	v_mfma_f32_16x16x32_bf16 v[106:109], v[178:181], v[214:217], v[106:109]
	v_mfma_f32_16x16x32_bf16 v[110:113], v[170:173], v[214:217], v[110:113]
	v_mfma_f32_16x16x32_bf16 v[110:113], v[166:169], v[206:209], v[110:113]
	v_mfma_f32_16x16x32_bf16 v[94:97], v[166:169], v[218:221], v[94:97]
	v_mfma_f32_16x16x32_bf16 v[94:97], v[170:173], v[222:225], v[94:97]
	v_mfma_f32_16x16x32_bf16 v[90:93], v[178:181], v[222:225], v[90:93]
	v_mfma_f32_16x16x32_bf16 v[90:93], v[174:177], v[218:221], v[90:93]
	v_mfma_f32_16x16x32_bf16 v[74:77], v[174:177], v[226:229], v[74:77]
	v_mfma_f32_16x16x32_bf16 v[74:77], v[178:181], v[230:233], v[74:77]
	v_mfma_f32_16x16x32_bf16 v[78:81], v[170:173], v[230:233], v[78:81]
	v_mfma_f32_16x16x32_bf16 v[78:81], v[166:169], v[226:229], v[78:81]
	v_mfma_f32_16x16x32_bf16 v[118:121], v[182:185], v[198:201], v[118:121]
	v_mfma_f32_16x16x32_bf16 v[118:121], v[186:189], v[202:205], v[118:121]
	v_mfma_f32_16x16x32_bf16 v[114:117], v[194:197], v[202:205], v[114:117]
	v_mfma_f32_16x16x32_bf16 v[114:117], v[190:193], v[198:201], v[114:117]
	v_mfma_f32_16x16x32_bf16 v[98:101], v[190:193], v[206:209], v[98:101]
	v_mfma_f32_16x16x32_bf16 v[98:101], v[194:197], v[214:217], v[98:101]
	v_mfma_f32_16x16x32_bf16 v[102:105], v[186:189], v[214:217], v[102:105]
	v_mfma_f32_16x16x32_bf16 v[102:105], v[182:185], v[206:209], v[102:105]
	v_mfma_f32_16x16x32_bf16 v[86:89], v[182:185], v[218:221], v[86:89]
	v_mfma_f32_16x16x32_bf16 v[86:89], v[186:189], v[222:225], v[86:89]
	v_mfma_f32_16x16x32_bf16 v[82:85], v[194:197], v[222:225], v[82:85]
	v_mfma_f32_16x16x32_bf16 v[82:85], v[190:193], v[218:221], v[82:85]
	v_mfma_f32_16x16x32_bf16 v[66:69], v[190:193], v[226:229], v[66:69]
	v_mfma_f32_16x16x32_bf16 v[66:69], v[194:197], v[230:233], v[66:69]
	v_mfma_f32_16x16x32_bf16 v[70:73], v[186:189], v[230:233], v[70:73]
	v_mfma_f32_16x16x32_bf16 v[70:73], v[182:185], v[226:229], v[70:73]
	s_barrier
	s_mov_b32 m0, s43
	s_add_u32 s28, s28, 0x80
	s_addc_u32 s29, s29, 0
	ds_read_b128 v[198:201], v154 offset:49152
	ds_read_b128 v[202:205], v154 offset:50176
	ds_read_b128 v[206:209], v154 offset:51200
	ds_read_b128 v[214:217], v154 offset:52224
	ds_read_b128 v[218:221], v154 offset:53248
	ds_read_b128 v[222:225], v154 offset:54272
	ds_read_b128 v[226:229], v154 offset:55296
	ds_read_b128 v[230:233], v154 offset:56320
	global_load_lds_dwordx4 v132, s[28:29]
	s_mov_b32 m0, s44
	s_nop 0
	global_load_lds_dwordx4 v136, s[28:29]
	s_add_u32 s28, s28, 0x108000
	s_addc_u32 s29, s29, 0
	s_mov_b32 m0, s45
	s_nop 0
	global_load_lds_dwordx4 v132, s[28:29]
	s_mov_b32 m0, s46
	s_nop 0
	global_load_lds_dwordx4 v136, s[28:29]
	s_mov_b32 m0, s35
	s_nop 0
	global_load_lds_dwordx4 v130, s[26:27]
	s_mov_b32 m0, s36
	s_nop 0
	global_load_lds_dwordx4 v134, s[26:27]
	s_waitcnt vmcnt(8)
	s_waitcnt lgkmcnt(0)
	s_barrier
	s_waitcnt lgkmcnt(0)
	v_mfma_f32_16x16x32_bf16 v[62:65], v[166:169], v[198:201], v[62:65]
	v_mfma_f32_16x16x32_bf16 v[62:65], v[170:173], v[202:205], v[62:65]
	v_mfma_f32_16x16x32_bf16 v[58:61], v[178:181], v[202:205], v[58:61]
	v_mfma_f32_16x16x32_bf16 v[58:61], v[174:177], v[198:201], v[58:61]
	v_mfma_f32_16x16x32_bf16 v[42:45], v[174:177], v[206:209], v[42:45]
	v_mfma_f32_16x16x32_bf16 v[42:45], v[178:181], v[214:217], v[42:45]
	v_mfma_f32_16x16x32_bf16 v[46:49], v[170:173], v[214:217], v[46:49]
	v_mfma_f32_16x16x32_bf16 v[46:49], v[166:169], v[206:209], v[46:49]
	v_mfma_f32_16x16x32_bf16 v[30:33], v[166:169], v[218:221], v[30:33]
	v_mfma_f32_16x16x32_bf16 v[30:33], v[170:173], v[222:225], v[30:33]
	v_mfma_f32_16x16x32_bf16 v[26:29], v[178:181], v[222:225], v[26:29]
	v_mfma_f32_16x16x32_bf16 v[26:29], v[174:177], v[218:221], v[26:29]
	v_mfma_f32_16x16x32_bf16 v[10:13], v[174:177], v[226:229], v[10:13]
	v_mfma_f32_16x16x32_bf16 v[10:13], v[178:181], v[230:233], v[10:13]
	v_mfma_f32_16x16x32_bf16 v[14:17], v[170:173], v[230:233], v[14:17]
	v_mfma_f32_16x16x32_bf16 v[14:17], v[166:169], v[226:229], v[14:17]
	v_mfma_f32_16x16x32_bf16 v[54:57], v[182:185], v[198:201], v[54:57]
	v_mfma_f32_16x16x32_bf16 v[54:57], v[186:189], v[202:205], v[54:57]
	v_mfma_f32_16x16x32_bf16 v[50:53], v[194:197], v[202:205], v[50:53]
	v_mfma_f32_16x16x32_bf16 v[50:53], v[190:193], v[198:201], v[50:53]
	v_mfma_f32_16x16x32_bf16 v[34:37], v[190:193], v[206:209], v[34:37]
	v_mfma_f32_16x16x32_bf16 v[34:37], v[194:197], v[214:217], v[34:37]
	v_mfma_f32_16x16x32_bf16 v[38:41], v[186:189], v[214:217], v[38:41]
	v_mfma_f32_16x16x32_bf16 v[38:41], v[182:185], v[206:209], v[38:41]
	v_mfma_f32_16x16x32_bf16 v[22:25], v[182:185], v[218:221], v[22:25]
	v_mfma_f32_16x16x32_bf16 v[22:25], v[186:189], v[222:225], v[22:25]
	v_mfma_f32_16x16x32_bf16 v[18:21], v[194:197], v[222:225], v[18:21]
	v_mfma_f32_16x16x32_bf16 v[18:21], v[190:193], v[218:221], v[18:21]
	v_mfma_f32_16x16x32_bf16 v[2:5], v[190:193], v[226:229], v[2:5]
	v_mfma_f32_16x16x32_bf16 v[2:5], v[194:197], v[230:233], v[2:5]
	v_mfma_f32_16x16x32_bf16 v[6:9], v[186:189], v[230:233], v[6:9]
	v_mfma_f32_16x16x32_bf16 v[6:9], v[182:185], v[226:229], v[6:9]
	s_barrier
	s_add_i32 s54, s54, 2
	s_add_u32 s22, s22, 0x100
	s_addc_u32 s23, s23, 0
	s_cmp_gt_u32 s54, 61
	s_cbranch_scc0 .LBB0_612
	s_and_b64 vcc, exec, s[16:17]
	s_cbranch_vccz .LBB0_615
	s_barrier
